# A-head attention loop: selection-bitmask words fetched as one dwordx4 per 4 key tiles instead of one dword per tile; plus earlier attention/bisection/sp4/nt changes
# speedup vs baseline: 1.1806x; 1.0042x over previous
; #define LAS __attribute__((address_space(3)))
; template <int MODE>
; DI void attn_range(const AttnCtx& c, const bf16x8 (&qf)[4], int lo, int hi, int t0, int d00, AttnSt& st, const unsigned* maskrow, int h8, int win, int dmask, bool lane_sel) {
;     if (lo > hi) return;
;     attn_dma(c, lo);
;     unsigned Wn = 0u;
;     if (MODE == 0) Wn = maskrow[lo];
; #pragma unroll 1
;     for (int kt = lo; kt <= hi; ++kt) {
;         asm volatile("s_waitcnt vmcnt(0)" ::: "memory");
;         bf16x8 kf[4], vf[2][2];
; #pragma unroll
;         for (int ks = 0; ks < 4; ++ks) kf[ks] = *(const LAS bf16x8*)(c.wl + c.kfo[ks]);
; #pragma unroll
;         for (int mt = 0; mt < 2; ++mt)
; #pragma unroll
;             for (int s = 0; s < 2; ++s) vf[mt][s] = *(const LAS bf16x8*)(c.wl + 4096 + c.vfo[mt][s]);
;         const unsigned W = Wn >> h8;
;         const int dlo = t0 - kt * 32 - 31;
;         float ub = 0.f; bool uni = false;
;         if (dlo >= 182) { const unsigned ua = __builtin_amdgcn_readfirstlane(__float_as_uint(c.lut[dlo])), ue = __builtin_amdgcn_readfirstlane(__float_as_uint(c.lut[dlo + 62])); uni = (ua == ue); ub = __uint_as_float(ua); }
; DI void attn_job(const Args& a, unsigned char* wsh, LAS unsigned char* wl, int type, int b, int qt, int hd, const int tid) {
;     ...
;     AttnSt st; st.m = NEGF; st.l = 0.f;
; #pragma unroll
;     for (int i = 0; i < 16; ++i) { st.o0[i] = 0.f; st.o1[i] = 0.f; }
;     const int ng = (type == 1) ? 2 : 1;
;     int ocol = 0;
;     for (int g = 0; g < ng; ++g) {
;         int qcol, kcol, vrow, bcol;
;         if (type == 0) { qcol = C_AQ + hd * 64; kcol = C_AK; vrow = R_AV; bcol = hd; ocol = hd * 64; }
;         else if (type == 1) { qcol = C_BQ + (g * 4 + hd) * 64; kcol = C_BK + hd * 64; vrow = R_BV + hd * 64; bcol = 6 + g * 4 + hd; ocol = 384 + hd * 64; }
;         else { qcol = C_CQ + hd * 64; kcol = C_CK + hd * 64; vrow = R_CV + hd * 64; bcol = 18 + hd; ocol = 640 + hd * 64; }
;         load_lut(lut, glut, bcol, lane);
;         bf16x8 qf[4];
;         const bf16_t* qp = prm + (size_t)(tok0 + t0 + r) * RM_LD + qcol + 8 * h;
; #pragma unroll
;         for (int ks = 0; ks < 4; ++ks) qf[ks] = *(const bf16x8*)(qp + 16 * ks);
;         c.kg = prm + (size_t)tok0 * RM_LD + kcol;
;         c.vg = prt + (size_t)vrow * MTOK + tok0;
;         if (type == 0) {
;             attn_range<0>(c, qf, 0, qt, t0, d00, st, maskrow, h8, 0, 0, false);
.LBB0_319:
	s_and_b64 vcc, exec, s[0:1]
	s_cbranch_vccz .LBB0_269
	s_lshl_b32 s8, s57, 5
	s_lshl_b32 s4, s56, 11
	s_add_i32 s60, s8, s4
	v_or_b32_e32 v98, s60, v135
	s_movk_i32 s0, 0x1600
	v_mad_i64_i32 v[94:95], s[0:1], v98, s0, v[132:133]
	s_ashr_i32 s5, s4, 31
	v_readlane_b32 s6, v254, 55
	s_mul_hi_i32 s1, s4, 0x1600
	v_readlane_b32 s7, v254, 56
	s_add_u32 s0, s6, s59
	s_addc_u32 s1, s7, s1
	s_lshl_b64 s[4:5], s[4:5], 1
	v_readlane_b32 s6, v251, 21
	v_readlane_b32 s7, v251, 22
	s_add_u32 s4, s6, s4
	s_addc_u32 s5, s7, s5
	s_lshl_b32 s2, s58, 13
	v_lshl_add_u64 v[96:97], v[130:131], 0, s[2:3]
	v_add_co_u32_e32 v30, vcc, s94, v96
	s_nop 1
	v_addc_co_u32_e32 v31, vcc, 0, v97, vcc
	global_load_dwordx4 v[2:5], v[96:97], off
	global_load_dwordx4 v[6:9], v[96:97], off offset:1024
	global_load_dwordx4 v[10:13], v[96:97], off offset:2048
	global_load_dwordx4 v[14:17], v[96:97], off offset:3072
	global_load_dwordx4 v[18:21], v[30:31], off
	global_load_dwordx4 v[22:25], v[30:31], off offset:1024
	global_load_dwordx4 v[26:29], v[30:31], off offset:2048
	s_nop 0
	global_load_dwordx4 v[30:33], v[30:31], off offset:3072
	s_lshl_b32 s6, s58, 6
	v_ashrrev_i32_e32 v99, 31, v98
	s_cmp_lt_i32 s57, 0
	v_add_u32_e32 v104, s8, v161
	v_mov_b32_e32 v102, 0
	s_mov_b64 s[64:65], 0x300
	s_waitcnt vmcnt(0)
	ds_write_b128 v143, v[2:5] offset:8192
	ds_write_b128 v143, v[6:9] offset:9216
	ds_write_b128 v143, v[10:13] offset:10240
	ds_write_b128 v143, v[14:17] offset:11264
	ds_write_b128 v143, v[18:21] offset:12288
	ds_write_b128 v143, v[22:25] offset:13312
	ds_write_b128 v143, v[26:29] offset:14336
	ds_write_b128 v143, v[30:33] offset:15360
	v_mov_b32_e32 v17, 0
	v_mov_b32_e32 v16, 0
	v_mov_b32_e32 v15, 0
	v_mov_b32_e32 v14, 0
	v_mov_b32_e32 v13, 0
	v_mov_b32_e32 v12, 0
	v_mov_b32_e32 v11, 0
	v_mov_b32_e32 v10, 0
	v_mov_b32_e32 v9, 0
	v_mov_b32_e32 v8, 0
	v_mov_b32_e32 v7, 0
	v_mov_b32_e32 v6, 0
	v_mov_b32_e32 v5, 0
	v_mov_b32_e32 v4, 0
	v_mov_b32_e32 v3, 0
	v_mov_b32_e32 v2, 0
	v_mov_b32_e32 v33, 0
	v_mov_b32_e32 v32, 0
	v_mov_b32_e32 v31, 0
	v_mov_b32_e32 v30, 0
	v_mov_b32_e32 v29, 0
	v_mov_b32_e32 v28, 0
	v_mov_b32_e32 v27, 0
	v_mov_b32_e32 v26, 0
	v_mov_b32_e32 v25, 0
	v_mov_b32_e32 v24, 0
	v_mov_b32_e32 v23, 0
	v_mov_b32_e32 v22, 0
	v_mov_b32_e32 v21, 0
	v_mov_b32_e32 v20, 0
	v_mov_b32_e32 v19, 0
	v_mov_b32_e32 v18, 0
	s_cbranch_scc1 .LBB0_329
	s_lshl_b32 s2, s6, 1
	v_lshl_add_u64 v[6:7], s[0:1], 0, v[116:117]
	s_mov_b32 m0, s49
	v_lshl_add_u64 v[4:5], v[94:95], 0, s[2:3]
	v_lshl_add_u64 v[6:7], v[6:7], 0, s[64:65]
	global_load_dwordx4 v[50:53], v[4:5], off offset:96
	global_load_dwordx4 v[54:57], v[4:5], off offset:64
	global_load_dwordx4 v[58:61], v[4:5], off offset:32
	s_add_i32 s7, s49, 0x400
	global_load_lds_dwordx4 v[6:7], off
	v_lshl_add_u64 v[6:7], s[0:1], 0, v[118:119]
	v_lshl_add_u64 v[6:7], v[6:7], 0, s[64:65]
	s_mov_b32 m0, s7
	s_add_i32 s9, s49, 0x800
	global_load_lds_dwordx4 v[6:7], off
	v_lshl_add_u64 v[6:7], s[0:1], 0, v[122:123]
	v_readlane_b32 s46, v251, 27
	v_lshl_add_u64 v[6:7], v[6:7], 0, s[64:65]
	s_mov_b32 m0, s9
	v_lshlrev_b64 v[2:3], 8, v[98:99]
	v_readlane_b32 s47, v251, 28
	global_load_lds_dwordx4 v[6:7], off
	v_lshl_add_u64 v[6:7], s[0:1], 0, v[126:127]
	v_lshl_add_u64 v[2:3], s[46:47], 0, v[2:3]
	v_lshl_add_u64 v[6:7], v[6:7], 0, s[64:65]
	s_mov_b32 m0, s53
	s_add_i32 s46, s49, 0x1000
	global_load_lds_dwordx4 v[6:7], off
	v_lshl_add_u64 v[6:7], s[4:5], 0, v[114:115]
	s_mov_b32 m0, s46
	s_add_i32 s47, s49, 0x1800
	global_load_lds_dwordx4 v[6:7], off
	v_lshl_add_u64 v[6:7], s[4:5], 0, v[120:121]
	s_mov_b32 m0, s54
	v_mov_b32_e32 v14, v1
	global_load_lds_dwordx4 v[6:7], off
	v_lshl_add_u64 v[6:7], s[4:5], 0, v[124:125]
	s_mov_b32 m0, s47
	v_mov_b32_e32 v15, v1
	global_load_lds_dwordx4 v[6:7], off
	global_load_dwordx4 v[62:65], v[4:5], off
	global_load_dwordx4 v[198:201], v[2:3], off
	v_lshl_add_u64 v[6:7], s[4:5], 0, v[128:129]
	s_mov_b32 m0, s55
	v_add_u32_e32 v2, s60, v135
	global_load_lds_dwordx4 v[6:7], off
	v_ashrrev_i32_e32 v3, 31, v2
	v_readlane_b32 s60, v253, 63
	v_lshlrev_b64 v[2:3], 8, v[2:3]
	v_readlane_b32 s61, v254, 0
	v_mov_b32_e32 v0, v1
	v_mov_b32_e32 v4, v1
	v_lshl_add_u64 v[100:101], s[60:61], 0, v[2:3]
	v_mov_b32_e32 v2, v1
	v_mov_b32_e32 v3, v1
	v_mov_b32_e32 v5, v1
	v_mov_b32_e32 v6, v1
	v_mov_b32_e32 v7, v1
	v_mov_b32_e32 v8, v1
	v_mov_b32_e32 v9, v1
	v_mov_b32_e32 v10, v1
	v_mov_b32_e32 v11, v1
	v_mov_b32_e32 v12, v1
	v_mov_b32_e32 v13, v1
	v_mov_b64_e32 v[32:33], v[14:15]
	v_mov_b64_e32 v[30:31], v[12:13]
	v_mov_b64_e32 v[28:29], v[10:11]
	v_mov_b64_e32 v[26:27], v[8:9]
	v_mov_b64_e32 v[24:25], v[6:7]
	v_mov_b64_e32 v[22:23], v[4:5]
	v_mov_b64_e32 v[20:21], v[2:3]
	v_mov_b64_e32 v[18:19], v[0:1]
	v_mov_b64_e32 v[16:17], v[14:15]
	s_add_i32 s59, s57, 1
	v_lshl_add_u32 v103, v104, 2, s51
	s_mov_b32 s60, 0
	v_mov_b32_e32 v105, 0xf149f2ca
	v_mov_b32_e32 v102, 0
	s_mov_b32 s2, 32
	v_mov_b64_e32 v[14:15], v[12:13]
	v_mov_b64_e32 v[12:13], v[10:11]
	v_mov_b64_e32 v[10:11], v[8:9]
	v_mov_b64_e32 v[8:9], v[6:7]
	v_mov_b64_e32 v[6:7], v[4:5]
	v_mov_b64_e32 v[4:5], v[2:3]
	v_mov_b64_e32 v[2:3], v[0:1]
	s_waitcnt vmcnt(0)
	v_mov_b32_e32 v106, v198
.LBB0_322:
	s_waitcnt vmcnt(0)
	ds_read_b128 v[34:37], v214
	ds_read_b128 v[90:93], v215
	ds_read_b128 v[86:89], v216
	ds_read_b128 v[82:85], v217
	ds_read_b128 v[78:81], v218 offset:4096
	ds_read_b128 v[70:73], v218 offset:6144
	ds_read_b128 v[74:77], v219 offset:4096
	ds_read_b128 v[66:69], v219 offset:6144
	s_waitcnt lgkmcnt(0)
	s_cmp_ge_i32 s60, s57
	s_cbranch_scc1 .LBB0_324
	s_add_i32 s61, s60, 1
	s_and_b32 s61, s61, 3
	s_cbranch_scc1 .Lmk_skip
	global_load_dwordx4 v[224:227], v[100:101], off
.Lmk_skip:
	s_mul_i32 s62, s2, 0x1600
	s_mul_hi_i32 s61, s2, 0x1600
	s_add_u32 s62, s0, s62
	s_addc_u32 s63, s1, s61
	s_add_u32 s62, s62, s64
	s_addc_u32 s63, s63, s65
	s_mov_b32 m0, s49
	s_nop 0
	global_load_lds_dwordx4 v116, s[62:63]
	s_mov_b32 m0, s7
	s_nop 0
	global_load_lds_dwordx4 v118, s[62:63]
	s_mov_b32 m0, s9
	s_nop 0
	global_load_lds_dwordx4 v122, s[62:63]
	s_mov_b32 m0, s53
	s_nop 0
	global_load_lds_dwordx4 v126, s[62:63]
	s_lshl_b64 s[62:63], s[2:3], 1
	s_add_u32 s62, s4, s62
	s_addc_u32 s63, s5, s63
	s_mov_b32 m0, s46
	s_nop 0
	global_load_lds_dwordx4 v114, s[62:63]
	s_mov_b32 m0, s54
	s_nop 0
	global_load_lds_dwordx4 v120, s[62:63]
	s_mov_b32 m0, s47
	s_nop 0
	global_load_lds_dwordx4 v124, s[62:63]
	s_mov_b32 m0, s55
	s_nop 0
	global_load_lds_dwordx4 v128, s[62:63]

; #define LAS __attribute__((address_space(3)))
; DI unsigned pk2(float lo, float hi) { f32x2 v = {lo, hi}; bf2_t b = __builtin_convertvector(v, bf2_t); return __builtin_bit_cast(unsigned, b); }
; template <int MODE, bool UNI>
; DI void attn_compute(const bf16x8 (&qf)[4], const bf16x8 (&kf)[4], const bf16x8 (&vf)[2][2], int kt, int d00, const float* lut, float ubias, AttnSt& st,
;                      unsigned W, int win, int dmask, bool lane_sel) {
;     ...
;     float ps = 0.f; float p[16];
; #pragma unroll
;     for (int i = 0; i < 16; ++i) { const float e = __builtin_amdgcn_exp2f(sv[i] - msafe); p[i] = e; ps += e; }
;     st.l += ps;
;     u32x4 w0, w1;
;     w0.x = pk2(p[0], p[1]); w0.y = pk2(p[2], p[3]); w0.z = pk2(p[4], p[5]); w0.w = pk2(p[6], p[7]);
;     w1.x = pk2(p[8], p[9]); w1.y = pk2(p[10], p[11]); w1.z = pk2(p[12], p[13]); w1.w = pk2(p[14], p[15]);
;     const bf16x8 pf0 = __builtin_bit_cast(bf16x8, w0), pf1 = __builtin_bit_cast(bf16x8, w1);
;     st.o0 = MFMA32(vf[0][0], pf0, st.o0); st.o0 = MFMA32(vf[0][1], pf1, st.o0);
;     st.o1 = MFMA32(vf[1][0], pf0, st.o1); st.o1 = MFMA32(vf[1][1], pf1, st.o1);
; template <int MODE>
; DI void attn_range(const AttnCtx& c, const bf16x8 (&qf)[4], int lo, int hi, int t0, int d00, AttnSt& st, const unsigned* maskrow, int h8, int win, int dmask, bool lane_sel) {
;     ...
;     unsigned Wn = 0u;
;     if (MODE == 0) Wn = maskrow[lo];
; #pragma unroll 1
;     for (int kt = lo; kt <= hi; ++kt) {
;         asm volatile("s_waitcnt vmcnt(0)" ::: "memory");
;         bf16x8 kf[4], vf[2][2];
; #pragma unroll
;         for (int ks = 0; ks < 4; ++ks) kf[ks] = *(const LAS bf16x8*)(c.wl + c.kfo[ks]);
; #pragma unroll
;         for (int mt = 0; mt < 2; ++mt)
; #pragma unroll
;             for (int s = 0; s < 2; ++s) vf[mt][s] = *(const LAS bf16x8*)(c.wl + 4096 + c.vfo[mt][s]);
;         const unsigned W = Wn >> h8;
;         const int dlo = t0 - kt * 32 - 31;
;         float ub = 0.f; bool uni = false;
;         if (dlo >= 182) { const unsigned ua = __builtin_amdgcn_readfirstlane(__float_as_uint(c.lut[dlo])), ue = __builtin_amdgcn_readfirstlane(__float_as_uint(c.lut[dlo + 62])); uni = (ua == ue); ub = __uint_as_float(ua); }
;         asm volatile("s_waitcnt lgkmcnt(0)" ::: "memory");
;         if (kt < hi) { attn_dma(c, kt + 1); if (MODE == 0) Wn = maskrow[kt + 1]; }
.LBB0_327:
	v_sub_f32_e32 v38, v38, v36
	v_exp_f32_e32 v86, v38
	v_sub_f32_e32 v38, v40, v36
	v_exp_f32_e32 v87, v38
	v_sub_f32_e32 v38, v41, v36
	v_sub_f32_e32 v48, v85, v36
	v_sub_f32_e32 v49, v84, v36
	v_sub_f32_e32 v83, v83, v36
	v_sub_f32_e32 v82, v82, v36
	v_sub_f32_e32 v39, v39, v36
	v_sub_f32_e32 v37, v37, v36
	v_exp_f32_e32 v88, v38
	v_sub_f32_e32 v38, v42, v36
	v_exp_f32_e32 v48, v48
	v_exp_f32_e32 v49, v49
	v_exp_f32_e32 v83, v83
	v_exp_f32_e32 v82, v82
	v_exp_f32_e32 v85, v39
	v_exp_f32_e32 v37, v37
	v_exp_f32_e32 v89, v38
	v_sub_f32_e32 v38, v43, v36
	v_exp_f32_e32 v90, v38
	v_sub_f32_e32 v38, v44, v36
	v_exp_f32_e32 v91, v38
	v_sub_f32_e32 v38, v45, v36
	v_exp_f32_e32 v92, v38
	v_sub_f32_e32 v38, v46, v36
	v_add_f32_e32 v84, 0, v48
	v_exp_f32_e32 v46, v38
	v_cvt_pk_bf16_f32 v38, v48, v49
	v_cvt_pk_bf16_f32 v39, v83, v82
	v_cvt_pk_bf16_f32 v40, v85, v86
	v_cvt_pk_bf16_f32 v41, v37, v87
	v_add_f32_e32 v84, v49, v84
	v_add_f32_e32 v84, v83, v84
	v_mfma_f32_32x32x16_bf16 v[18:33], v[78:81], v[38:41], v[18:33]
	v_sub_f32_e32 v42, v47, v36
	v_sub_f32_e32 v35, v35, v36
	v_add_f32_e32 v36, v82, v84
	v_exp_f32_e32 v47, v42
	v_exp_f32_e32 v35, v35
	v_add_f32_e32 v36, v85, v36
	v_add_f32_e32 v36, v86, v36
	v_mfma_f32_32x32x16_bf16 v[2:17], v[70:73], v[38:41], v[2:17]
	v_add_f32_e32 v36, v37, v36
	v_add_f32_e32 v36, v87, v36
	v_cvt_pk_bf16_f32 v42, v88, v89
	v_cvt_pk_bf16_f32 v43, v90, v91
	v_cvt_pk_bf16_f32 v44, v92, v46
	v_cvt_pk_bf16_f32 v45, v47, v35
	v_add_f32_e32 v36, v88, v36
	v_add_f32_e32 v36, v89, v36
	v_mfma_f32_32x32x16_bf16 v[18:33], v[74:77], v[42:45], v[18:33]
	v_add_f32_e32 v36, v90, v36
	v_add_f32_e32 v36, v91, v36
	v_add_f32_e32 v36, v92, v36
	v_add_f32_e32 v36, v46, v36
	v_add_f32_e32 v36, v47, v36
	v_add_f32_e32 v35, v35, v36
	s_add_i32 s60, s60, 1
	v_mfma_f32_32x32x16_bf16 v[2:17], v[66:69], v[42:45], v[2:17]
	s_add_i32 s2, s2, 32
	v_add_f32_e32 v102, v35, v102
	v_lshl_add_u64 v[100:101], v[100:101], 0, 4
	s_cmp_lg_u32 s59, s60
	v_add_u32_e32 v103, 0xffffff80, v103
	s_cbranch_scc0 .LBB0_329
	v_mov_b32_e32 v105, v34
	s_and_b32 s61, s60, 3
	s_cbranch_scc1 .Lmk_rot
	s_waitcnt vmcnt(0)
	v_mov_b32_e32 v198, v224
	v_mov_b32_e32 v199, v225
	v_mov_b32_e32 v200, v226
	v_mov_b32_e32 v201, v227
	s_branch .Lmk_done
.Lmk_rot:
	v_mov_b32_e32 v198, v199
	v_mov_b32_e32 v199, v200
	v_mov_b32_e32 v200, v201
.Lmk_done:
	v_mov_b32_e32 v106, v198
	s_branch .LBB0_322
